# v23: v20 + scan K-transpose fragments via ds_read_b64_tr_b16 (replaces 48 ds_read_u16 + 24 v_lshl_or per step)
# speedup vs baseline: 1.0049x; 1.0049x over previous
.LBB0_445:
	s_or_b64 exec, exec, s[4:5]
	s_add_u32 s70, s90, 0x100000
	s_addc_u32 s71, s91, 0
	s_cmpk_lt_i32 s3, 0x100
	s_cselect_b64 s[4:5], -1, 0
	v_writelane_b32 v255, s4, 15
	s_waitcnt lgkmcnt(0)
	v_mov_b32_e32 v0, v146
	s_cmpk_gt_i32 s3, 0xff
	v_writelane_b32 v255, s5, 16
	s_movk_i32 s2, 0x100
	s_mov_b64 s[94:95], s[80:81]
	s_barrier
	s_cbranch_scc1 .LBB0_515
	v_add_u32_e32 v4, 0x200, v0
	v_ashrrev_i32_e32 v9, 7, v0
	v_and_b32_e32 v1, 15, v0
	v_lshlrev_b32_e32 v2, 3, v0
	v_ashrrev_i32_e32 v168, 5, v4
	v_add_u32_e32 v4, 0x400, v0
	v_lshlrev_b32_e32 v116, 4, v9
	v_ashrrev_i32_e32 v145, 5, v0
	v_and_b32_e32 v2, 0xf8, v2
	v_ashrrev_i32_e32 v170, 5, v4
	v_add_u32_e32 v4, 0x600, v0
	v_or_b32_e32 v10, v116, v1
	s_movk_i32 s8, 0x90
	v_ashrrev_i32_e32 v5, 6, v0
	v_ashrrev_i32_e32 v172, 5, v4
	v_lshlrev_b32_e32 v4, 1, v2
	s_movk_i32 s10, 0x210
	v_mul_lo_u32 v13, v10, s8
	s_movk_i32 s8, 0x480
	v_add_u32_e32 v19, 1, v145
	v_mul_lo_u32 v179, v5, s8
	v_cvt_f32_i32_e32 v180, v19
	v_mad_u64_u32 v[118:119], s[8:9], v145, s10, v[4:5]
	v_add_u32_e32 v19, 1, v168
	v_bfe_u32 v3, v0, 4, 2
	v_and_b32_e32 v129, 63, v0
	v_mov_b32_e32 v6, 0x10800
	v_and_b32_e32 v7, 0xffffffc0, v0
	v_lshlrev_b32_e32 v11, 1, v5
	v_cvt_f32_i32_e32 v119, v19
	v_mad_u64_u32 v[120:121], s[8:9], v168, s10, v[4:5]
	v_add_u32_e32 v19, 1, v170
	v_lshl_or_b32 v175, v129, 1, v6
	v_lshl_or_b32 v6, v3, 3, v7
	v_and_b32_e32 v12, 2, v11
	v_cvt_f32_i32_e32 v121, v19
	v_mad_u64_u32 v[122:123], s[8:9], v170, s10, v[4:5]
	v_add_u32_e32 v19, 1, v172
	v_add_u32_e32 v8, 0x15000, v6
	v_lshlrev_b32_e32 v6, 2, v3
	v_cvt_f32_i32_e32 v123, v19
	v_lshlrev_b32_e32 v19, 4, v12
	v_or_b32_e32 v22, v19, v6
	v_mul_lo_u32 v176, v10, s10
	v_mad_u64_u32 v[124:125], s[8:9], v172, s10, v[4:5]
	v_cmp_le_i32_e64 s[10:11], v12, v9
	v_cmp_lt_i32_e64 s[12:13], v12, v9
	v_or_b32_e32 v9, 16, v19
	v_or_b32_e32 v23, 2, v22
	s_movk_i32 s6, 0xff
	v_mov_b32_e32 v14, 0x1d400
	s_mov_b32 s22, 0x12c00
	v_or_b32_e32 v181, v9, v1
	v_cmp_gt_i32_e64 s[14:15], v22, v10
	v_cmp_lt_i32_e64 s[16:17], v22, v10
	v_cmp_gt_i32_e64 s[18:19], v23, v10
	v_or_b32_e32 v23, 3, v22
	v_lshlrev_b32_e32 v22, 1, v22
	v_or_b32_e32 v9, v9, v6
	v_bitop3_b32 v174, v0, s6, 63 bitop3:0x6c
	v_cmp_gt_i32_e64 s[6:7], s2, v0
	v_lshl_add_u32 v178, v0, 2, v14
	v_add_u32_e32 v0, 0x10800, v13
	s_add_u32 s33, s90, 0x6800800
	v_add3_u32 v182, v13, v22, s22
	v_or_b32_e32 v13, 2, v9
	v_lshlrev_b32_e32 v177, 4, v3
	v_lshlrev_b32_e32 v17, 1, v1
	v_or_b32_e32 v125, v19, v1
	v_or_b32_e32 v11, 1, v11
	s_addc_u32 s41, s91, 0
	v_cmp_gt_i32_e64 s[22:23], v9, v10
	v_cmp_lt_i32_e64 s[24:25], v9, v10
	v_cmp_gt_i32_e64 s[26:27], v13, v10
	v_or_b32_e32 v9, 3, v9
	s_movk_i32 s8, 0x21ff
	v_mov_b32_e32 v13, 0x20c0
	v_mov_b32_e32 v113, 0
	v_cmp_gt_i32_e64 s[4:5], 8, v5
	v_lshlrev_b32_e32 v114, 3, v5
	v_add_u32_e32 v14, 0x15000, v176
	v_or_b32_e32 v15, 0x12c00, v177
	v_or_b32_e32 v16, 0x10800, v177
	v_or_b32_e32 v18, 0x1d400, v177
	v_mul_u32_u24_e32 v4, 0x210, v1
	v_mul_u32_u24_e32 v20, 0x210, v125
	v_mul_u32_u24_e32 v12, 0x210, v181
	v_mul_u32_u24_e32 v21, 0x90, v1
	v_or_b32_e32 v7, v17, v7
	v_mul_u32_u24_e32 v3, 0x1080, v3
	v_lshlrev_b32_e32 v5, 7, v5
	v_lshl_or_b32 v17, v11, 5, v17
	v_lshlrev_b32_e32 v11, 6, v11
	v_cmp_gt_i32_e64 s[20:21], v23, v10
	v_cmp_gt_i32_e64 s[28:29], v9, v10
	v_mul_u32_u24_e32 v9, 0x90, v125
	v_mul_u32_u24_e32 v10, 0x90, v181
	s_add_u32 s42, s90, 0x17000000
	v_bitop3_b32 v184, v125, s8, v13 bitop3:0x36
	v_bitop3_b32 v186, v181, s8, v13 bitop3:0x36
	s_movk_i32 s8, 0x21ef
	v_sub_u32_e32 v167, 0xff, v145
	v_sub_u32_e32 v169, 0xff, v168
	v_sub_u32_e32 v171, 0xff, v170
	v_sub_u32_e32 v173, 0xff, v172
	v_ashrrev_i32_e32 v115, 31, v114
	v_ashrrev_i32_e32 v117, 31, v116
	s_addc_u32 s43, s91, 0
	v_or_b32_e32 v183, 0x20c0, v125
	v_or_b32_e32 v185, 0x20c0, v181
	v_bitop3_b32 v187, v19, s8, v1 bitop3:0x36
	v_or_b32_e32 v188, 64, v129
	v_add_u32_e32 v189, 64, v172
	v_add_u32_e32 v190, 64, v170
	v_add_u32_e32 v191, 64, v168
	v_add_u32_e32 v192, 64, v145
	s_mov_b32 s67, 0
	v_lshlrev_b32_e32 v126, 1, v2
	v_mov_b32_e32 v127, v113
	v_lshlrev_b32_e32 v112, 1, v6
	v_add_u32_e32 v193, v16, v21
	v_add_u32_e32 v196, v7, v3
	v_add_u32_e32 v197, v18, v5
	v_add_u32_e32 v198, v17, v3
	v_add_u32_e32 v199, v18, v11
	v_add_u32_e32 v200, v8, v4
	v_add_u32_e32 v201, v177, v20
	v_add_u32_e32 v202, v177, v12
	v_add_u32_e32 v203, v0, v177
	v_add_u32_e32 v204, v14, v177
	v_add_u32_e32 v205, v15, v9
	v_add_u32_e32 v206, v15, v10
	v_lshrrev_b32_e32 v0, 2, v1
	v_and_b32_e32 v2, 3, v1
	v_mul_u32_u24_e32 v0, 0x210, v0
	v_lshl_add_u32 v0, v2, 3, v0
	v_lshlrev_b32_e32 v2, 1, v1
	v_sub_u32_e32 v0, v0, v2
	v_add_u32_e32 v196, v196, v0
	s_mov_b32 s40, s3
	s_branch .LBB0_448

.LBB0_505:
	v_cmp_gt_i32_e32 vcc, s2, v72
	v_add_u32_e32 v74, 0xffffff00, v72
	v_ashrrev_i32_e32 v73, 31, v72
	v_cndmask_b32_e32 v72, v74, v72, vcc
	v_mov_b32_e32 v74, s9
	v_mov_b32_e32 v75, s39
	v_cndmask_b32_e32 v73, 0, v73, vcc
	v_cndmask_b32_e32 v75, v74, v75, vcc
	v_mov_b32_e32 v74, s8
	v_mov_b32_e32 v76, s38
	v_cndmask_b32_e32 v74, v74, v76, vcc
	v_lshlrev_b64 v[72:73], 12, v[72:73]
	v_lshl_add_u64 v[72:73], v[74:75], 0, v[72:73]
	v_lshl_add_u64 v[72:73], v[116:117], 1, v[72:73]
	v_lshl_add_u64 v[72:73], v[72:73], 0, v[112:113]
	v_cvt_pk_bf16_f32 v68, v68, v69
	v_cvt_pk_bf16_f32 v69, v70, v71
	global_store_dwordx2 v[72:73], v[68:69], off
	ds_read_b128 v[96:99], v193
	ds_read_b128 v[80:83], v193 offset:64
	ds_read_b128 v[92:95], v193 offset:2304
	ds_read_b128 v[76:79], v193 offset:2368
	ds_read_b128 v[88:91], v193 offset:4608
	ds_read_b128 v[68:71], v193 offset:4672
	ds_read_b128 v[84:87], v193 offset:6912
	ds_read_b128 v[72:75], v193 offset:6976
	ds_read_b64_tr_b16 v[100:101], v196 offset:33792
	ds_read_b64_tr_b16 v[102:103], v196 offset:35904
	ds_read_b64_tr_b16 v[104:105], v196 offset:50688
	ds_read_b64_tr_b16 v[106:107], v196 offset:52800
	s_add_i32 s54, s54, 64
	s_waitcnt lgkmcnt(2)
	v_mfma_f32_16x16x32_bf16 v[12:15], v[100:103], v[96:99], v[12:15]
	v_subrev_u32_e32 v208, 64, v208
	s_cmpk_eq_i32 s54, 0x20c0
	v_mfma_f32_16x16x32_bf16 v[16:19], v[100:103], v[92:95], v[16:19]
	v_mfma_f32_16x16x32_bf16 v[8:11], v[100:103], v[88:91], v[8:11]
	v_mfma_f32_16x16x32_bf16 v[4:7], v[100:103], v[84:87], v[4:7]
	ds_read_b128 v[100:103], v197
	s_waitcnt lgkmcnt(1)
	v_mfma_f32_16x16x32_bf16 v[12:15], v[104:107], v[80:83], v[12:15]
	v_mfma_f32_16x16x32_bf16 v[16:19], v[104:107], v[76:79], v[16:19]
	v_mfma_f32_16x16x32_bf16 v[8:11], v[104:107], v[68:71], v[8:11]
	s_waitcnt lgkmcnt(0)
	s_nop 4
	v_pk_mul_f32 v[14:15], v[14:15], v[102:103]
	v_pk_mul_f32 v[12:13], v[12:13], v[100:101]
	v_pk_mul_f32 v[18:19], v[18:19], v[102:103]
	v_mfma_f32_16x16x32_bf16 v[4:7], v[104:107], v[72:75], v[4:7]
	v_mul_f32_e64 v16, v16, v100
	v_mul_f32_e64 v17, v17, v101
	v_pk_mul_f32 v[10:11], v[10:11], v[102:103]
	v_pk_mul_f32 v[8:9], v[8:9], v[100:101]
	s_nop 3
	v_pk_mul_f32 v[6:7], v[6:7], v[102:103]
	v_pk_mul_f32 v[4:5], v[4:5], v[100:101]
	ds_read_b64_tr_b16 v[100:101], v196 offset:33824
	ds_read_b64_tr_b16 v[102:103], v196 offset:35936
	ds_read_b64_tr_b16 v[104:105], v196 offset:50720
	ds_read_b64_tr_b16 v[106:107], v196 offset:52832
	s_waitcnt lgkmcnt(2)
	v_mfma_f32_16x16x32_bf16 v[24:27], v[100:103], v[88:91], v[24:27]
	v_mfma_f32_16x16x32_bf16 v[32:35], v[100:103], v[96:99], v[32:35]
	v_mfma_f32_16x16x32_bf16 v[28:31], v[100:103], v[92:95], v[28:31]
	v_mfma_f32_16x16x32_bf16 v[20:23], v[100:103], v[84:87], v[20:23]
	s_waitcnt lgkmcnt(0)
	v_mfma_f32_16x16x32_bf16 v[24:27], v[104:107], v[68:71], v[24:27]
	ds_read_b128 v[68:71], v199
	s_waitcnt lgkmcnt(0)
	s_barrier
	v_mfma_f32_16x16x32_bf16 v[32:35], v[104:107], v[80:83], v[32:35]
	s_nop 3
	v_mul_f32_e64 v26, v26, v70
	v_mul_f32_e64 v27, v27, v71
	v_pk_mul_f32 v[24:25], v[24:25], v[68:69]
	v_mfma_f32_16x16x32_bf16 v[28:31], v[104:107], v[76:79], v[28:31]
	v_mfma_f32_16x16x32_bf16 v[20:23], v[104:107], v[72:75], v[20:23]
	v_mul_f32_e64 v34, v34, v70
	v_mul_f32_e64 v35, v35, v71
	v_pk_mul_f32 v[32:33], v[32:33], v[68:69]
	s_nop 3
	v_pk_mul_f32 v[30:31], v[30:31], v[70:71]
	v_pk_mul_f32 v[28:29], v[28:29], v[68:69]
	v_pk_mul_f32 v[22:23], v[22:23], v[70:71]
	v_pk_mul_f32 v[20:21], v[20:21], v[68:69]
	s_cbranch_scc0 .LBB0_455
	s_and_saveexec_b64 s[34:35], s[6:7]
	ds_write_b32 v178, v207
	s_or_b64 exec, exec, s[34:35]
	s_waitcnt vmcnt(9)
	v_lshlrev_b32_e32 v68, 16, v64
	v_and_b32_e32 v69, 0xffff0000, v64
	v_pk_mul_f32 v[68:69], v[152:153], v[68:69]
	s_nop 0
	v_cvt_pk_bf16_f32 v64, v68, v69
	v_lshlrev_b32_e32 v68, 16, v65
	v_and_b32_e32 v69, 0xffff0000, v65
	v_pk_mul_f32 v[68:69], v[152:153], v[68:69]
	s_nop 0
	v_cvt_pk_bf16_f32 v65, v68, v69
	v_lshlrev_b32_e32 v68, 16, v66
	v_and_b32_e32 v69, 0xffff0000, v66
	v_pk_mul_f32 v[68:69], v[152:153], v[68:69]
	s_nop 0
	v_cvt_pk_bf16_f32 v66, v68, v69
	v_lshlrev_b32_e32 v68, 16, v67
	v_and_b32_e32 v69, 0xffff0000, v67
	v_pk_mul_f32 v[68:69], v[152:153], v[68:69]
	s_nop 0
	v_cvt_pk_bf16_f32 v67, v68, v69
	s_waitcnt vmcnt(8)
	v_lshlrev_b32_e32 v68, 16, v60
	v_and_b32_e32 v69, 0xffff0000, v60
	v_pk_mul_f32 v[68:69], v[150:151], v[68:69]
	s_nop 0
	v_cvt_pk_bf16_f32 v60, v68, v69
	v_lshlrev_b32_e32 v68, 16, v61
	v_and_b32_e32 v69, 0xffff0000, v61
	v_pk_mul_f32 v[68:69], v[150:151], v[68:69]
	s_nop 0
	v_cvt_pk_bf16_f32 v61, v68, v69
	v_lshlrev_b32_e32 v68, 16, v62
	v_and_b32_e32 v69, 0xffff0000, v62
	v_pk_mul_f32 v[68:69], v[150:151], v[68:69]
	s_nop 0
	v_cvt_pk_bf16_f32 v62, v68, v69
	v_lshlrev_b32_e32 v68, 16, v63
	v_and_b32_e32 v69, 0xffff0000, v63
	v_pk_mul_f32 v[68:69], v[150:151], v[68:69]
	s_nop 0
	v_cvt_pk_bf16_f32 v63, v68, v69
	ds_write_b128 v118, v[64:67]
	ds_write_b128 v118, v[60:63] offset:33792
	s_waitcnt vmcnt(7)
	v_lshlrev_b32_e32 v60, 16, v56
	v_and_b32_e32 v61, 0xffff0000, v56
	v_pk_mul_f32 v[60:61], v[142:143], v[60:61]
	s_nop 0
	v_cvt_pk_bf16_f32 v56, v60, v61
	v_lshlrev_b32_e32 v60, 16, v57
	v_and_b32_e32 v61, 0xffff0000, v57
	v_pk_mul_f32 v[60:61], v[142:143], v[60:61]
	s_nop 0
	v_cvt_pk_bf16_f32 v57, v60, v61
	v_lshlrev_b32_e32 v60, 16, v58
	v_and_b32_e32 v61, 0xffff0000, v58
	v_pk_mul_f32 v[60:61], v[142:143], v[60:61]
	s_nop 0
	v_cvt_pk_bf16_f32 v58, v60, v61
	v_lshlrev_b32_e32 v60, 16, v59
	v_and_b32_e32 v61, 0xffff0000, v59
	v_pk_mul_f32 v[60:61], v[142:143], v[60:61]
	s_nop 0
	v_cvt_pk_bf16_f32 v59, v60, v61
	s_waitcnt vmcnt(6)
	v_lshlrev_b32_e32 v60, 16, v52
	v_and_b32_e32 v61, 0xffff0000, v52
	v_pk_mul_f32 v[60:61], v[140:141], v[60:61]
	s_nop 0
	v_cvt_pk_bf16_f32 v52, v60, v61
	v_lshlrev_b32_e32 v60, 16, v53
	v_and_b32_e32 v61, 0xffff0000, v53
	v_pk_mul_f32 v[60:61], v[140:141], v[60:61]
	s_nop 0
	v_cvt_pk_bf16_f32 v53, v60, v61
	v_lshlrev_b32_e32 v60, 16, v54
	v_and_b32_e32 v61, 0xffff0000, v54
	v_pk_mul_f32 v[60:61], v[140:141], v[60:61]
	s_nop 0
	v_cvt_pk_bf16_f32 v54, v60, v61
	v_lshlrev_b32_e32 v60, 16, v55
	v_and_b32_e32 v61, 0xffff0000, v55
	v_pk_mul_f32 v[60:61], v[140:141], v[60:61]
	s_nop 0
	v_cvt_pk_bf16_f32 v55, v60, v61
	ds_write_b128 v120, v[56:59]
	ds_write_b128 v120, v[52:55] offset:33792
	s_waitcnt vmcnt(5)
	v_lshlrev_b32_e32 v52, 16, v48
	v_and_b32_e32 v53, 0xffff0000, v48
	v_pk_mul_f32 v[52:53], v[138:139], v[52:53]
	s_nop 0
	v_cvt_pk_bf16_f32 v48, v52, v53
	v_lshlrev_b32_e32 v52, 16, v49
	v_and_b32_e32 v53, 0xffff0000, v49
	v_pk_mul_f32 v[52:53], v[138:139], v[52:53]
	s_nop 0
	v_cvt_pk_bf16_f32 v49, v52, v53
	v_lshlrev_b32_e32 v52, 16, v50
	v_and_b32_e32 v53, 0xffff0000, v50
	v_pk_mul_f32 v[52:53], v[138:139], v[52:53]
	s_nop 0
	v_cvt_pk_bf16_f32 v50, v52, v53
	v_lshlrev_b32_e32 v52, 16, v51
	v_and_b32_e32 v53, 0xffff0000, v51
	v_pk_mul_f32 v[52:53], v[138:139], v[52:53]
	s_nop 0
	v_cvt_pk_bf16_f32 v51, v52, v53
	s_waitcnt vmcnt(4)
	v_lshlrev_b32_e32 v52, 16, v44
	v_and_b32_e32 v53, 0xffff0000, v44
	v_pk_mul_f32 v[52:53], v[136:137], v[52:53]
	s_nop 0
	v_cvt_pk_bf16_f32 v44, v52, v53
	v_lshlrev_b32_e32 v52, 16, v45
	v_and_b32_e32 v53, 0xffff0000, v45
	v_pk_mul_f32 v[52:53], v[136:137], v[52:53]
	s_nop 0
	v_cvt_pk_bf16_f32 v45, v52, v53
	v_lshlrev_b32_e32 v52, 16, v46
	v_and_b32_e32 v53, 0xffff0000, v46
	v_pk_mul_f32 v[52:53], v[136:137], v[52:53]
	s_nop 0
	v_cvt_pk_bf16_f32 v46, v52, v53
	v_lshlrev_b32_e32 v52, 16, v47
	v_and_b32_e32 v53, 0xffff0000, v47
	v_pk_mul_f32 v[52:53], v[136:137], v[52:53]
	s_nop 0
	v_cvt_pk_bf16_f32 v47, v52, v53
	ds_write_b128 v122, v[48:51]
	ds_write_b128 v122, v[44:47] offset:33792
	s_waitcnt vmcnt(3)
	v_lshlrev_b32_e32 v44, 16, v40
	v_and_b32_e32 v45, 0xffff0000, v40
	v_pk_mul_f32 v[44:45], v[134:135], v[44:45]
	s_nop 0
	v_cvt_pk_bf16_f32 v40, v44, v45
	v_lshlrev_b32_e32 v44, 16, v41
	v_and_b32_e32 v45, 0xffff0000, v41
	v_pk_mul_f32 v[44:45], v[134:135], v[44:45]
	s_nop 0
	v_cvt_pk_bf16_f32 v41, v44, v45
	v_lshlrev_b32_e32 v44, 16, v42
	v_and_b32_e32 v45, 0xffff0000, v42
	v_pk_mul_f32 v[44:45], v[134:135], v[44:45]
	s_nop 0
	v_cvt_pk_bf16_f32 v42, v44, v45
	v_lshlrev_b32_e32 v44, 16, v43
	v_and_b32_e32 v45, 0xffff0000, v43
	v_pk_mul_f32 v[44:45], v[134:135], v[44:45]
	s_nop 0
	v_cvt_pk_bf16_f32 v43, v44, v45
	s_waitcnt vmcnt(2)
	v_lshlrev_b32_e32 v44, 16, v36
	v_and_b32_e32 v45, 0xffff0000, v36
	v_pk_mul_f32 v[44:45], v[132:133], v[44:45]
	s_nop 0
	v_cvt_pk_bf16_f32 v36, v44, v45
	v_lshlrev_b32_e32 v44, 16, v37
	v_and_b32_e32 v45, 0xffff0000, v37
	v_pk_mul_f32 v[44:45], v[132:133], v[44:45]
	s_nop 0
	v_cvt_pk_bf16_f32 v37, v44, v45
	v_lshlrev_b32_e32 v44, 16, v38
	v_and_b32_e32 v45, 0xffff0000, v38
	v_pk_mul_f32 v[44:45], v[132:133], v[44:45]
	s_nop 0
	v_cvt_pk_bf16_f32 v38, v44, v45
	v_lshlrev_b32_e32 v44, 16, v39
	v_and_b32_e32 v45, 0xffff0000, v39
	v_pk_mul_f32 v[44:45], v[132:133], v[44:45]
	s_nop 0
	v_cvt_pk_bf16_f32 v39, v44, v45
	ds_write_b128 v124, v[40:43]
	ds_write_b128 v124, v[36:39] offset:33792
	s_and_saveexec_b64 s[34:35], s[4:5]
	s_cbranch_execz .LBB0_510
	v_add_u32_e32 v36, v175, v179
	ds_write_b16 v36, v0
	ds_write_b16_d16_hi v36, v0 offset:144
	ds_write_b16 v36, v1 offset:288
	ds_write_b16_d16_hi v36, v1 offset:432
	ds_write_b16 v36, v2 offset:576
	ds_write_b16_d16_hi v36, v2 offset:720
	ds_write_b16 v36, v3 offset:864
	ds_write_b16_d16_hi v36, v3 offset:1008

.LBB0_3302:
	s_or_b64 exec, exec, s[0:1]
	v_readlane_b32 s0, v255, 23
	v_readlane_b32 s1, v255, 24
	s_waitcnt lgkmcnt(0)
	v_mov_b32_e32 v0, v146
	s_and_b64 vcc, exec, s[0:1]
	s_barrier
	s_cbranch_vccnz .LBB0_3410
	v_lshlrev_b32_e32 v2, 1, v0
	v_and_b32_e32 v36, 0x7e, v2
	v_ashrrev_i32_e32 v2, 3, v0
	v_ashrrev_i32_e32 v3, 6, v0
	v_and_b32_e32 v37, 63, v0
	v_and_b32_e32 v90, -8, v2
	v_or_b32_e32 v104, 7, v2
	v_mov_b32_e32 v2, 0x11600
	v_and_b32_e32 v1, 15, v0
	v_lshl_add_u32 v107, v0, 3, v2
	v_lshlrev_b32_e32 v4, 1, v37
	v_lshlrev_b32_e32 v2, 2, v37
	v_ashrrev_i32_e32 v8, 7, v0
	v_lshlrev_b32_e32 v13, 4, v3
	s_movk_i32 s0, 0xff
	v_sub_u32_e32 v108, v2, v4
	v_lshl_or_b32 v9, v8, 4, v1
	s_movk_i32 s1, 0x110
	v_lshlrev_b32_e32 v4, 1, v3
	v_and_b32_e32 v13, 48, v13
	v_bfe_u32 v5, v0, 4, 2
	v_bitop3_b32 v106, v0, s0, 63 bitop3:0x6c
	v_mul_lo_u32 v109, v9, s1
	v_and_b32_e32 v10, 2, v4
	s_movk_i32 s1, 0x480
	v_bitop3_b32 v115, v13, s0, v1 bitop3:0x36
	s_movk_i32 s0, 0x880
	v_cmp_gt_i32_e64 s[6:7], 4, v3
	v_lshlrev_b32_e32 v40, 3, v3
	v_cmp_eq_u32_e64 s[8:9], 7, v3
	v_lshlrev_b32_e32 v6, 5, v3
	v_lshlrev_b32_e32 v4, 2, v5
	v_mul_lo_u32 v112, v3, s1
	v_cmp_lt_i32_e64 s[10:11], 0, v3
	v_cmp_lt_i32_e64 s[12:13], 1, v3
	v_cmp_lt_i32_e64 s[14:15], 2, v3
	v_cmp_lt_i32_e64 s[16:17], 3, v3
	v_cmp_lt_i32_e64 s[18:19], 4, v3
	v_cmp_lt_i32_e64 s[20:21], 5, v3
	v_cmp_lt_i32_e64 s[22:23], 6, v3
	v_mad_u64_u32 v[44:45], s[4:5], v3, s0, v[2:3]
	v_lshlrev_b32_e32 v3, 4, v10
	v_lshlrev_b32_e32 v11, 7, v9
	v_ashrrev_i32_e32 v12, 4, v0
	v_cmp_le_i32_e64 s[24:25], v10, v8
	v_or_b32_e32 v16, v3, v1
	v_cmp_lt_i32_e64 s[26:27], v10, v8
	v_or_b32_e32 v8, 16, v3
	v_or_b32_e32 v3, v3, v4
	v_sub_u32_e32 v11, v109, v11
	v_and_b32_e32 v42, -16, v12
	v_bfi_b32 v12, -16, v12, v0
	s_movk_i32 s1, 0x90
	v_or_b32_e32 v114, v13, v1
	v_mul_u32_u24_e32 v45, 0x110, v16
	s_add_u32 s2, s90, 0xb400800
	v_or_b32_e32 v16, 2, v3
	v_mul_lo_u32 v113, v12, s1
	v_lshlrev_b32_e32 v15, 7, v114
	v_and_b32_e32 v0, 0xffffffc0, v0
	v_or_b32_e32 v10, v8, v1
	s_addc_u32 s33, s91, 0
	v_cmp_gt_i32_e64 s[28:29], v3, v9
	v_cmp_lt_i32_e64 s[30:31], v3, v9
	v_cmp_gt_i32_e64 s[34:35], v16, v9
	v_or_b32_e32 v16, 3, v3
	v_lshl_add_u32 v118, v3, 1, v11
	v_or_b32_e32 v3, v8, v4
	s_movk_i32 s0, 0x13f
	s_mov_b32 s58, s52
	v_mov_b32_e32 v39, 0
	v_or_b32_e32 v92, 1, v90
	v_or_b32_e32 v94, 2, v90
	v_or_b32_e32 v96, 3, v90
	v_or_b32_e32 v98, 4, v90
	v_or_b32_e32 v100, 5, v90
	v_or_b32_e32 v102, 6, v90
	v_lshl_or_b32 v7, v5, 3, v6
	v_lshlrev_b32_e32 v110, 4, v5
	v_lshlrev_b32_e32 v111, 3, v37
	v_lshl_add_u32 v12, v12, 7, v113
	v_mul_u32_u24_e32 v14, 0x90, v114
	v_mad_u32_u24 v15, v114, s1, v15
	v_lshl_or_b32 v6, v1, 1, v6
	v_add_u32_e32 v0, 0x11400, v0
	v_mul_u32_u24_e32 v2, 0x110, v1
	v_mul_u32_u24_e32 v117, 0x110, v10
	v_mul_u32_u24_e32 v10, 0x90, v1
	v_mul_u32_u24_e32 v5, 0x880, v5
	s_add_u32 s52, s90, 0xb401800
	v_lshlrev_b32_e32 v38, 1, v36
	v_cmp_gt_i32_e64 s[38:39], v3, v9
	v_cmp_lt_i32_e64 s[40:41], v3, v9
	v_or_b32_e32 v8, 2, v3
	v_or_b32_e32 v3, 3, v3
	v_bitop3_b32 v119, v13, s0, v1 bitop3:0x36
	s_movk_i32 s0, 0x21ff
	v_sub_u32_e32 v91, 0xff, v90
	v_sub_u32_e32 v93, 0xff, v92
	v_sub_u32_e32 v95, 0xff, v94
	v_sub_u32_e32 v97, 0xff, v96
	v_sub_u32_e32 v99, 0xff, v98
	v_sub_u32_e32 v101, 0xff, v100
	v_sub_u32_e32 v103, 0xff, v102
	v_sub_u32_e32 v105, 0xff, v104
	v_ashrrev_i32_e32 v41, 31, v40
	v_ashrrev_i32_e32 v43, 31, v42
	s_mov_b32 s1, 0
	v_or_b32_e32 v116, 0x11600, v111
	s_addc_u32 s53, s91, 0
	v_lshl_add_u64 v[46:47], s[56:57], 0, v[38:39]
	v_cmp_gt_i32_e64 s[36:37], v16, v9
	v_cmp_gt_i32_e64 s[42:43], v8, v9
	v_cmp_gt_i32_e64 s[44:45], v3, v9
	v_or_b32_e32 v120, 0x20c0, v114
	v_bitop3_b32 v121, v13, s0, v1 bitop3:0x36
	v_or_b32_e32 v122, 64, v37
	v_add_u32_e32 v123, 64, v104
	v_lshlrev_b32_e32 v48, 1, v36
	v_mov_b32_e32 v49, v39
	s_movk_i32 s60, 0x2800
	v_mov_b32_e32 v50, 1.0
	v_lshlrev_b32_e32 v52, 1, v4
	v_add_u32_e32 v124, v110, v10
	v_add_u32_e32 v125, v0, v110
	v_add_u32_e32 v126, v6, v5
	v_add_u32_e32 v127, v7, v2
	v_add_u32_e32 v128, v12, v110
	v_add_u32_e32 v129, v14, v110
	v_add_u32_e32 v130, v15, v110
	v_mov_b32_e32 v131, 0x80000
	v_lshrrev_b32_e32 v0, 2, v1
	v_and_b32_e32 v2, 3, v1
	v_mul_u32_u24_e32 v0, 0x110, v0
	v_lshl_add_u32 v0, v2, 3, v0
	v_lshlrev_b32_e32 v2, 1, v1
	v_sub_u32_e32 v0, v0, v2
	v_add_u32_e32 v126, v126, v0
	s_mov_b32 s61, s3
	s_branch .LBB0_3305

.LBB0_3386:
	s_or_b64 exec, exec, s[4:5]
	s_waitcnt lgkmcnt(4)
	s_nop 5
	v_cndmask_b32_e64 v16, v12, 0, s[38:39]
	v_cndmask_b32_e64 v13, 0, v13, s[40:41]
	v_cndmask_b32_e64 v12, v16, v12, s[40:41]
	v_cndmask_b32_e64 v14, v14, 0, s[42:43]
	v_cndmask_b32_e64 v15, v15, 0, s[44:45]
	v_cvt_pk_bf16_f32 v12, v12, v13
	v_cvt_pk_bf16_f32 v13, v14, v15
	v_add_u32_e32 v89, v113, v110
	ds_write_b64 v118, v[12:13] offset:44064
	s_waitcnt lgkmcnt(0)
	s_barrier
	ds_read_b128 v[12:15], v89 offset:34880
	ds_read_b128 v[16:19], v89 offset:34816
	ds_read_b128 v[20:23], v128 offset:53440
	ds_read_b128 v[24:27], v128 offset:53376
	ds_read_b128 v[28:31], v128 offset:53312
	ds_read_b128 v[32:35], v128 offset:53248
	s_waitcnt lgkmcnt(4)
	s_waitcnt lgkmcnt(0)
	ds_read_b128 v[80:83], v129 offset:44096
	ds_read_b128 v[84:87], v129 offset:44032
	ds_read_b128 v[138:141], v130 offset:192
	ds_read_b128 v[154:157], v130 offset:128
	ds_read_b128 v[158:161], v130 offset:64
	ds_read_b128 v[162:165], v130
	s_waitcnt lgkmcnt(4)
	s_waitcnt lgkmcnt(0)
	v_mfma_f32_16x16x32_bf16 v[16:19], v[16:19], v[84:87], 0
	s_cmp_lt_u32 s67, 4
	s_cselect_b64 vcc, -1, 0
	s_movk_i32 s4, 0x100
	v_mfma_f32_16x16x32_bf16 v[12:15], v[12:15], v[80:83], v[16:19]
	v_mfma_f32_16x16x32_bf16 v[12:15], v[32:35], v[162:165], v[12:15]
	s_nop 2
	v_add_u32_e32 v16, s66, v114
	v_cndmask_b32_e32 v17, v132, v133, vcc
	v_cndmask_b32_e64 v16, v17, v16, s[46:47]
	v_mfma_f32_16x16x32_bf16 v[12:15], v[28:31], v[158:161], v[12:15]
	v_add_u32_e32 v18, 0xffffff00, v16
	v_ashrrev_i32_e32 v17, 31, v16
	v_cmp_gt_i32_e32 vcc, s4, v16
	v_mfma_f32_16x16x32_bf16 v[12:15], v[24:27], v[154:157], v[12:15]
	s_add_i32 s66, s66, 64
	v_cndmask_b32_e32 v17, 0, v17, vcc
	v_cndmask_b32_e32 v16, v18, v16, vcc
	v_cndmask_b32_e64 v38, v131, 0, vcc
	v_lshl_add_u64 v[18:19], s[54:55], 0, v[38:39]
	v_lshlrev_b64 v[16:17], 11, v[16:17]
	v_mfma_f32_16x16x32_bf16 v[12:15], v[20:23], v[138:141], v[12:15]
	v_lshl_add_u64 v[138:139], v[18:19], 0, v[16:17]
	ds_read_b128 v[16:19], v124 offset:34816
	ds_read_b128 v[20:23], v124 offset:34880
	ds_read_b128 v[24:27], v124 offset:37120
	ds_read_b128 v[28:31], v124 offset:37184
	ds_read_b64_tr_b16 v[80:81], v126 offset:17408
	ds_read_b64_tr_b16 v[82:83], v126 offset:18496
	ds_read_b128 v[32:35], v125
	ds_read_b64_tr_b16 v[84:85], v126 offset:26112
	ds_read_b64_tr_b16 v[86:87], v126 offset:27200
	s_waitcnt lgkmcnt(3)
	v_mfma_f32_16x16x32_bf16 v[4:7], v[80:83], v[16:19], v[4:7]
	s_waitcnt lgkmcnt(0)
	v_lshl_add_u64 v[16:17], v[42:43], 1, v[138:139]
	v_mov_b32_e32 v53, v39
	v_mfma_f32_16x16x32_bf16 v[8:11], v[80:83], v[24:27], v[8:11]
	v_lshl_add_u64 v[16:17], v[16:17], 0, v[52:53]
	v_cvt_pk_bf16_f32 v12, v12, v13
	v_cvt_pk_bf16_f32 v13, v14, v15
	global_store_dwordx2 v[16:17], v[12:13], off
	s_waitcnt vmcnt(16)
	v_lshlrev_b32_e32 v13, 16, v51
	v_and_b32_e32 v14, 0xffff0000, v51
	v_mul_f32_e32 v13, 0xbfb8aa3b, v13
	v_exp_f32_e32 v15, v13
	v_mul_f32_e32 v13, 0xbfb8aa3b, v14
	v_mfma_f32_16x16x32_bf16 v[4:7], v[84:87], v[20:23], v[4:7]
	v_exp_f32_e32 v16, v13
	v_add_f32_e32 v14, 1.0, v15
	s_waitcnt vmcnt(14)
	v_and_b32_e32 v17, 0xffff0000, v66
	v_mfma_f32_16x16x32_bf16 v[8:11], v[84:87], v[28:31], v[8:11]
	v_add_f32_e32 v15, 1.0, v16
	s_nop 1
	v_pk_mul_f32 v[4:5], v[32:33], v[4:5]
	v_lshlrev_b32_e32 v16, 16, v66
	v_mul_f32_e32 v16, 0xbfb8aa3b, v16
	v_rcp_f32_e32 v14, v14
	s_nop 0
	v_pk_mul_f32 v[8:9], v[32:33], v[8:9]
	s_waitcnt vmcnt(8)
	v_lshlrev_b32_e32 v32, 16, v72
	v_and_b32_e32 v33, 0xffff0000, v72
	v_mul_f32_e32 v32, 0xbfb8aa3b, v32
	v_rcp_f32_e32 v15, v15
	v_exp_f32_e32 v16, v16
	v_mul_f32_e32 v17, 0xbfb8aa3b, v17
	v_lshlrev_b32_e32 v22, 16, v68
	v_exp_f32_e32 v38, v32
	v_mul_f32_e32 v32, 0xbfb8aa3b, v33
	v_exp_f32_e32 v17, v17
	v_and_b32_e32 v23, 0xffff0000, v68
	v_mul_f32_e32 v22, 0xbfb8aa3b, v22
	v_lshlrev_b32_e32 v26, 16, v70
	v_exp_f32_e32 v51, v32
	v_exp_f32_e32 v24, v22
	v_mul_f32_e32 v22, 0xbfb8aa3b, v23
	v_and_b32_e32 v27, 0xffff0000, v70
	v_mul_f32_e32 v26, 0xbfb8aa3b, v26
	v_exp_f32_e32 v25, v22
	v_exp_f32_e32 v30, v26
	v_mul_f32_e32 v26, 0xbfb8aa3b, v27
	v_pk_fma_f32 v[18:19], v[60:61], v[14:15], v[54:55]
	v_add_f32_e32 v14, 1.0, v16
	v_exp_f32_e32 v31, v26
	v_add_f32_e32 v38, 1.0, v38
	v_lshlrev_b32_e32 v12, 16, v64
	v_and_b32_e32 v13, 0xffff0000, v64
	v_rcp_f32_e32 v20, v14
	v_add_f32_e32 v14, 1.0, v17
	v_rcp_f32_e32 v64, v38
	v_add_f32_e32 v38, 1.0, v51
	v_rcp_f32_e32 v21, v14
	v_lshlrev_b32_e32 v14, 16, v65
	v_and_b32_e32 v15, 0xffff0000, v65
	v_rcp_f32_e32 v65, v38
	s_waitcnt vmcnt(6)
	v_lshlrev_b32_e32 v38, 16, v74
	v_add_f32_e32 v24, 1.0, v24
	v_add_f32_e32 v25, 1.0, v25
	v_and_b32_e32 v51, 0xffff0000, v74
	v_mul_f32_e32 v38, 0xbfb8aa3b, v38
	v_rcp_f32_e32 v24, v24
	v_rcp_f32_e32 v25, v25
	v_add_f32_e32 v30, 1.0, v30
	v_add_f32_e32 v31, 1.0, v31
	v_exp_f32_e32 v38, v38
	v_mul_f32_e32 v51, 0xbfb8aa3b, v51
	v_rcp_f32_e32 v30, v30
	v_rcp_f32_e32 v31, v31
	v_exp_f32_e32 v51, v51
	v_pk_fma_f32 v[20:21], v[60:61], v[20:21], v[54:55]
	v_pk_fma_f32 v[24:25], v[60:61], v[24:25], v[54:55]
	v_pk_mul_f32 v[28:29], v[18:19], v[20:21]
	v_add_f32_e32 v38, 1.0, v38
	v_pk_mul_f32 v[6:7], v[34:35], v[6:7]
	v_pk_mul_f32 v[10:11], v[34:35], v[10:11]
	v_pk_mul_f32 v[34:35], v[28:29], v[24:25]
	v_pk_fma_f32 v[30:31], v[60:61], v[30:31], v[54:55]
	v_rcp_f32_e32 v70, v38
	v_add_f32_e32 v38, 1.0, v51
	v_pk_add_f32 v[26:27], v[24:25], 1.0 op_sel_hi:[1,0] neg_lo:[1,0] neg_hi:[1,0]
	v_lshlrev_b32_e32 v24, 16, v69
	v_and_b32_e32 v25, 0xffff0000, v69
	v_pk_add_f32 v[32:33], v[30:31], 1.0 op_sel_hi:[1,0] neg_lo:[1,0] neg_hi:[1,0]
	v_pk_mul_f32 v[68:69], v[34:35], v[30:31]
	v_lshlrev_b32_e32 v30, 16, v71
	v_and_b32_e32 v31, 0xffff0000, v71
	v_rcp_f32_e32 v71, v38
	s_waitcnt vmcnt(4)
	v_lshlrev_b32_e32 v38, 16, v77
	v_and_b32_e32 v51, 0xffff0000, v77
	v_mul_f32_e32 v38, 0xbfb8aa3b, v38
	v_exp_f32_e32 v38, v38
	v_mul_f32_e32 v51, 0xbfb8aa3b, v51
	v_exp_f32_e32 v51, v51
	v_pk_add_f32 v[22:23], v[20:21], 1.0 op_sel_hi:[1,0] neg_lo:[1,0] neg_hi:[1,0]
	v_add_f32_e32 v38, 1.0, v38
	v_rcp_f32_e32 v80, v38
	v_add_f32_e32 v38, 1.0, v51
	v_rcp_f32_e32 v81, v38
	s_waitcnt vmcnt(2)
	v_lshlrev_b32_e32 v38, 16, v79
	v_and_b32_e32 v51, 0xffff0000, v79
	v_mul_f32_e32 v38, 0xbfb8aa3b, v38
	v_exp_f32_e32 v38, v38
	v_mul_f32_e32 v51, 0xbfb8aa3b, v51
	v_exp_f32_e32 v51, v51
	v_lshlrev_b32_e32 v20, 16, v67
	v_add_f32_e32 v38, 1.0, v38
	v_rcp_f32_e32 v86, v38
	v_add_f32_e32 v38, 1.0, v51
	v_rcp_f32_e32 v87, v38
	v_and_b32_e32 v21, 0xffff0000, v67
	v_pk_fma_f32 v[66:67], v[60:61], v[64:65], v[54:55]
	v_pk_fma_f32 v[70:71], v[60:61], v[70:71], v[54:55]
	v_pk_mul_f32 v[74:75], v[68:69], v[66:67]
	v_pk_add_f32 v[64:65], v[66:67], 1.0 op_sel_hi:[1,0] neg_lo:[1,0] neg_hi:[1,0]
	v_lshlrev_b32_e32 v66, 16, v73
	v_and_b32_e32 v67, 0xffff0000, v73
	v_pk_add_f32 v[72:73], v[70:71], 1.0 op_sel_hi:[1,0] neg_lo:[1,0] neg_hi:[1,0]
	v_pk_mul_f32 v[82:83], v[74:75], v[70:71]
	v_lshlrev_b32_e32 v70, 16, v76
	v_and_b32_e32 v71, 0xffff0000, v76
	v_pk_fma_f32 v[76:77], v[60:61], v[80:81], v[54:55]
	v_pk_fma_f32 v[86:87], v[60:61], v[86:87], v[54:55]
	v_pk_mul_f32 v[84:85], v[82:83], v[76:77]
	v_pk_add_f32 v[16:17], v[18:19], 1.0 op_sel_hi:[1,0] neg_lo:[1,0] neg_hi:[1,0]
	v_pk_add_f32 v[80:81], v[76:77], 1.0 op_sel_hi:[1,0] neg_lo:[1,0] neg_hi:[1,0]
	s_waitcnt vmcnt(1)
	v_lshlrev_b32_e32 v76, 16, v78
	v_and_b32_e32 v77, 0xffff0000, v78
	v_pk_add_f32 v[78:79], v[86:87], 1.0 op_sel_hi:[1,0] neg_lo:[1,0] neg_hi:[1,0]
	v_pk_mul_f32 v[86:87], v[84:85], v[86:87]
	v_subrev_u32_e32 v133, 64, v133
	s_cmpk_eq_i32 s66, 0x20c0
	v_subrev_u32_e32 v132, 64, v132
	ds_write_b64 v107, v[86:87]
	s_waitcnt lgkmcnt(0)
	s_barrier
	s_cbranch_scc0 .LBB0_3308
	v_mov_b32_e32 v51, v50
	v_mov_b64_e32 v[54:55], v[50:51]
	s_and_saveexec_b64 s[4:5], s[10:11]
	s_cbranch_execz .LBB0_3395
	ds_read_b64 v[54:55], v116
	s_or_b64 exec, exec, s[4:5]
	s_and_saveexec_b64 s[4:5], s[12:13]
	s_cbranch_execnz .LBB0_3396
